# UP helpers: tiles 4..9 of XCD 0 (earliest finishers) plus 4 per remote XCD
# speedup vs baseline: 1.0004x; 1.0004x over previous
; DI const bf16_t* wp(const Params& p, int l, size_t off) { return (const bf16_t*)(p.ws + OFF_WP) + (size_t)l * PW_LAYER + off; }
; template <int MT> DI void phaseB(const Params& p, int l, int t, unsigned char* lds) {
;     ...
;     EpiUp<MT> eu; eu.priv = priv; eu.d2 = d2;
;     eu.halo = (float*)(ws + OFF_UHALO) + (size_t)t * 2 * DFF2;
;     eu.pconv = t == NTILE - 1 ? p.out + O_PCONV + (size_t)l * 2 * DFF2 : nullptr;
;     eu.sconv = p.out + O_SCONV + ((size_t)l * 8 + 2 * t) * 2 * DFF2;
;     gemm64<1024, MT>(xb, DM, d2, wp(p, l, PW_UP), DFF2 / UW, lds, eu);
.LBB0_705:
	v_readlane_b32 s0, v254, 57
	s_nop 3
	s_cmp_lt_u32 s0, 4
	s_cbranch_scc1 .Lhu_done
	s_cmp_lt_u32 s0, 10
	s_cbranch_scc1 .Lhu_sel
	s_and_b32 s0, s0, 31
	s_cmp_gt_u32 s0, 3
	s_cbranch_scc1 .Lhu_done
.Lhu_sel:
	v_writelane_b32 v180, s0, 0
	v_writelane_b32 v180, s1, 1
	v_writelane_b32 v180, s2, 2
	v_writelane_b32 v180, s3, 3
	v_writelane_b32 v180, s4, 4
	v_writelane_b32 v180, s5, 5
	v_writelane_b32 v180, s6, 6
	v_writelane_b32 v180, s7, 7
	v_writelane_b32 v180, s8, 8
	v_writelane_b32 v180, s9, 9
	v_writelane_b32 v180, s10, 10
	v_writelane_b32 v180, s11, 11
	v_writelane_b32 v180, s12, 12
	v_writelane_b32 v180, s13, 13
	v_writelane_b32 v180, s14, 14
	v_writelane_b32 v180, s15, 15
	v_writelane_b32 v180, s16, 16
	v_writelane_b32 v180, s17, 17
	v_writelane_b32 v180, s18, 18
	v_writelane_b32 v180, s19, 19
	v_writelane_b32 v180, s20, 20
	v_writelane_b32 v180, s21, 21
	v_writelane_b32 v180, s22, 22
	v_writelane_b32 v180, s23, 23
	v_writelane_b32 v180, s24, 24
	v_writelane_b32 v180, s25, 25
	v_writelane_b32 v180, s26, 26
	v_writelane_b32 v180, s27, 27
	v_writelane_b32 v180, s28, 28
	v_writelane_b32 v180, s29, 29
	v_writelane_b32 v180, s30, 30
	v_writelane_b32 v180, s31, 31
	v_writelane_b32 v180, s32, 32
	v_writelane_b32 v180, s33, 33
	v_writelane_b32 v180, s34, 34
	v_writelane_b32 v180, s35, 35
	v_writelane_b32 v180, s36, 36
	v_writelane_b32 v180, s37, 37
	v_writelane_b32 v180, s38, 38
	v_writelane_b32 v180, s39, 39
	v_writelane_b32 v180, s40, 40
	v_writelane_b32 v180, s41, 41
	v_writelane_b32 v180, s42, 42
	v_writelane_b32 v180, s43, 43
	v_writelane_b32 v180, s44, 44
	v_writelane_b32 v180, s45, 45
	v_writelane_b32 v180, s46, 46
	v_writelane_b32 v180, s47, 47
	v_writelane_b32 v180, s48, 48
	v_writelane_b32 v180, s49, 49
	v_writelane_b32 v180, s50, 50
	v_writelane_b32 v180, s51, 51
	v_writelane_b32 v180, s52, 52
	v_writelane_b32 v180, s53, 53
	v_writelane_b32 v180, s54, 54
	v_writelane_b32 v180, s55, 55
	v_writelane_b32 v180, s56, 56
	v_writelane_b32 v180, s57, 57
	v_writelane_b32 v180, s58, 58
	v_writelane_b32 v180, s59, 59
	v_writelane_b32 v180, s60, 60
	v_writelane_b32 v180, s61, 61
	v_writelane_b32 v180, s62, 62
	v_writelane_b32 v180, s63, 63
	v_writelane_b32 v181, s64, 0
	v_writelane_b32 v181, s65, 1
	v_writelane_b32 v181, s66, 2
	v_writelane_b32 v181, s67, 3
	v_writelane_b32 v181, s68, 4
	v_writelane_b32 v181, s69, 5
	v_writelane_b32 v181, s70, 6
	v_writelane_b32 v181, s71, 7
	v_writelane_b32 v181, s72, 8
	v_writelane_b32 v181, s73, 9
	v_writelane_b32 v181, s74, 10
	v_writelane_b32 v181, s75, 11
	v_writelane_b32 v181, s76, 12
	v_writelane_b32 v181, s77, 13
	v_writelane_b32 v181, s78, 14
	v_writelane_b32 v181, s79, 15
	v_writelane_b32 v181, s80, 16
	v_writelane_b32 v181, s81, 17
	v_writelane_b32 v181, s82, 18
	v_writelane_b32 v181, s83, 19
	v_writelane_b32 v181, s84, 20
	v_writelane_b32 v181, s85, 21
	v_writelane_b32 v181, s86, 22
	v_writelane_b32 v181, s87, 23
	v_writelane_b32 v181, s88, 24
	v_writelane_b32 v181, s89, 25
	v_writelane_b32 v181, s90, 26
	v_writelane_b32 v181, s91, 27
	v_writelane_b32 v181, s92, 28
	v_writelane_b32 v181, s93, 29
	v_writelane_b32 v181, s94, 30
	v_writelane_b32 v181, s95, 31
	v_writelane_b32 v181, s96, 32
	v_writelane_b32 v181, s97, 33
	v_writelane_b32 v181, s98, 34
	v_writelane_b32 v181, s99, 35
	v_writelane_b32 v181, s100, 36
	v_writelane_b32 v181, s101, 37
	v_writelane_b32 v181, vcc_lo, 38
	v_writelane_b32 v181, vcc_hi, 39
	s_getreg_b32 s70, hwreg(HW_REG_XCC_ID, 0, 4)
	s_mov_b32 s43, 0xb0000
	s_movk_i32 s44, 0x1600
	s_mov_b32 s65, 0
	v_readlane_b32 s66, v252, 10
	v_readlane_b32 s67, v252, 11
	v_readlane_b32 s68, v254, 57
	s_mov_b32 s69, 0
	s_mov_b32 s80, 0
	v_lshrrev_b32_e32 v223, 6, v176
